# attention k-loop address hoist, fixed: post-loop tile write uses hoisted sum instead of loop temporaries (numerics identical to previous best again)
# baseline (speedup 1.0000x reference)
; DEV unsigned pack2(float a, float b) { f32x2 v = {a, b}; return __builtin_bit_cast(unsigned, __builtin_convertvector(v, bf2_t)); }
; DEV f32x16 mfma32(bf16x8 a, bf16x8 b, f32x16 c) { return __builtin_amdgcn_mfma_f32_32x32x16_bf16(a, b, c, 0, 0, 0); }
; DEV void attn_item(const Params& p, int item, char* smem) {
;     ...
;       const float mcur = mrun[jt];
;       float pv[16];
; #pragma unroll
;       for (int r = 0; r < 16; r++) pv[r] = __builtin_amdgcn_exp2f(s[jt][r] - mcur);
;       lrun[jt] += (((pv[0] + pv[1]) + (pv[2] + pv[3])) + ((pv[4] + pv[5]) + (pv[6] + pv[7]))) +
;                   (((pv[8] + pv[9]) + (pv[10] + pv[11])) + ((pv[12] + pv[13]) + (pv[14] + pv[15])));
;       bf16x8 pf[2];
; #pragma unroll
;       for (int ss = 0; ss < 2; ss++) {
;         uint4 u; u.x = pack2(pv[8 * ss + 0], pv[8 * ss + 1]); u.y = pack2(pv[8 * ss + 2], pv[8 * ss + 3]);
;         u.z = pack2(pv[8 * ss + 4], pv[8 * ss + 5]); u.w = pack2(pv[8 * ss + 6], pv[8 * ss + 7]);
;         pf[ss] = __builtin_bit_cast(bf16x8, u);
;       }
; #pragma unroll
;       for (int dt = 0; dt < 2; dt++)
; #pragma unroll
;         for (int ss = 0; ss < 2; ss++) {
;           uint2 lo = *(const uint2*)(Vc + (dt * 32 + c31) * VSTR + 16 * ss + 4 * hf);
;           uint2 hi = *(const uint2*)(Vc + (dt * 32 + c31) * VSTR + 16 * ss + 8 + 4 * hf);
;           uint4 u; u.x = lo.x; u.y = lo.y; u.z = hi.x; u.w = hi.y;
;           o[dt][jt] = mfma32(__builtin_bit_cast(bf16x8, u), pf[ss], o[dt][jt]);
;         }
;     }
;     if (kt + 1 < ntile) {
;       bf16_t* Kn = Ks + ((kt + 1) & 1) * (32 * ASTR);
;       bf16_t* Vn = Vs + ((kt + 1) & 1) * (64 * VSTR);
;       *(u32x4*)(Kn + k0row * ASTR + k0cc * 8) = rk0;
;       if (has_k1) *(u32x4*)(Kn + k1row * ASTR + k1cc * 8) = rk1;
;       *(uint2*)(Vn + vrow * VSTR + vcc * 8) = make_uint2(rv0[0], rv0[1]);
;       *(uint2*)(Vn + vrow * VSTR + vcc * 8 + 4) = make_uint2(rv0[2], rv0[3]);
.LBB0_763:
	v_sub_f32_e32 v80, v80, v175
	v_exp_f32_e32 v176, v80
	v_sub_f32_e32 v80, v81, v175
	v_exp_f32_e32 v178, v80
	v_sub_f32_e32 v80, v82, v175
	v_exp_f32_e32 v179, v80
	v_sub_f32_e32 v80, v83, v175
	v_exp_f32_e32 v180, v80
	v_sub_f32_e32 v80, v84, v175
	v_exp_f32_e32 v181, v80
	v_sub_f32_e32 v80, v85, v175
	v_exp_f32_e32 v182, v80
	v_sub_f32_e32 v80, v86, v175
	v_exp_f32_e32 v183, v80
	v_sub_f32_e32 v80, v87, v175
	v_exp_f32_e32 v190, v80
	v_sub_f32_e32 v80, v88, v175
	v_exp_f32_e32 v189, v80
	v_sub_f32_e32 v80, v89, v175
	v_exp_f32_e32 v191, v80
	v_sub_f32_e32 v80, v90, v175
	v_exp_f32_e32 v193, v80
	v_sub_f32_e32 v80, v91, v175
	v_exp_f32_e32 v194, v80
	v_sub_f32_e32 v80, v92, v175
	v_exp_f32_e32 v239, v80
	v_sub_f32_e32 v80, v93, v175
	v_exp_f32_e32 v240, v80
	v_sub_f32_e32 v80, v94, v175
	v_exp_f32_e32 v241, v80
	v_sub_f32_e32 v80, v95, v175
	v_exp_f32_e32 v243, v80
	v_cvt_pk_bf16_f32 v80, v176, v178
	v_cvt_pk_bf16_f32 v81, v179, v180
	v_cvt_pk_bf16_f32 v82, v181, v182
	v_cvt_pk_bf16_f32 v83, v183, v190
	v_cvt_pk_bf16_f32 v84, v189, v191
	v_cvt_pk_bf16_f32 v85, v193, v194
	v_mfma_f32_32x32x16_bf16 v[64:79], v[2:5], v[80:83], v[64:79]
	v_cvt_pk_bf16_f32 v86, v239, v240
	v_cvt_pk_bf16_f32 v87, v241, v243
	v_add_u32_e32 v2, s10, v214
	s_waitcnt vmcnt(2)
	ds_write_b128 v2, v[168:171]
	v_mfma_f32_32x32x16_bf16 v[48:63], v[10:13], v[80:83], v[48:63]
	v_mfma_f32_32x32x16_bf16 v[64:79], v[6:9], v[84:87], v[64:79]
	v_mfma_f32_32x32x16_bf16 v[48:63], v[96:99], v[84:87], v[48:63]
	s_and_saveexec_b64 s[8:9], s[38:39]
	s_cbranch_execz .LBB0_765
	v_lshlrev_b32_e32 v2, 1, v174
	v_add3_u32 v2, s10, v188, v2
	s_waitcnt vmcnt(1)
	ds_write_b128 v2, v[164:167]
